# P0: gain loads hoisted out of rows loop, on top of x loads nt
# speedup vs baseline: 1.0085x; 1.0085x over previous
.LBB0_38:
	s_add_i32 s28, s56, s58
	s_cmpk_lt_i32 s28, 0x4000
	s_cselect_b32 s16, s28, s56
	s_ashr_i32 s57, s56, 31
	s_lshl_b64 s[46:47], s[56:57], 12
	v_lshl_add_u64 v[34:35], v[2:3], 0, s[46:47]
	s_ashr_i32 s17, s16, 31
	global_load_dwordx4 v[22:25], v[34:35], off nt
	global_load_dwordx4 v[26:29], v[34:35], off offset:1024 nt
	global_load_dwordx4 v[30:33], v[34:35], off offset:3072 nt
	s_nop 0
	global_load_dwordx4 v[34:37], v[34:35], off offset:2048 nt
	s_lshl_b64 s[0:1], s[56:57], 10
	s_lshl_b64 s[50:51], s[16:17], 12
	s_lshl_b64 s[46:47], s[16:17], 10
	v_lshl_add_u64 v[38:39], v[6:7], 0, s[0:1]
	v_lshl_add_u64 v[64:65], v[2:3], 0, s[50:51]
	global_load_dwordx4 v[38:41], v[38:39], off nt
	v_lshl_add_u64 v[66:67], v[6:7], 0, s[46:47]
	global_load_dwordx4 v[42:45], v[64:65], off nt
	global_load_dwordx4 v[46:49], v[64:65], off offset:1024 nt
	global_load_dwordx4 v[50:53], v[64:65], off offset:3072 nt
	global_load_dwordx4 v[54:57], v[64:65], off offset:2048 nt
	global_load_dwordx4 v[58:61], v[66:67], off nt
	s_lshl_b64 s[0:1], s[16:17], 11
	v_lshl_add_u64 v[68:69], v[8:9], 0, s[0:1]
	s_lshl_b64 s[48:49], s[56:57], 11
	v_lshl_add_u64 v[62:63], v[8:9], 0, s[48:49]
	s_waitcnt vmcnt(9)
	v_pk_mul_f32 v[64:65], v[24:25], v[24:25]
	v_pk_mul_f32 v[66:67], v[22:23], v[22:23]
	s_waitcnt vmcnt(8)
	v_pk_mul_f32 v[70:71], v[28:29], v[28:29]
	v_pk_mul_f32 v[72:73], v[26:27], v[26:27]
	s_waitcnt vmcnt(6)
	v_mul_f32_e32 v74, v35, v35
	v_mul_f32_e32 v76, v37, v37
	v_pk_mov_b32 v[78:79], v[66:67], v[64:65] op_sel:[1,0]
	v_mov_b32_e32 v67, v65
	s_waitcnt vmcnt(4)
	v_pk_mul_f32 v[64:65], v[44:45], v[44:45]
	v_pk_mul_f32 v[80:81], v[42:43], v[42:43]
	v_pk_mov_b32 v[82:83], v[72:73], v[70:71] op_sel:[1,0]
	v_mov_b32_e32 v73, v71
	s_waitcnt vmcnt(3)
	v_pk_mul_f32 v[70:71], v[48:49], v[48:49]
	v_pk_mul_f32 v[84:85], v[46:47], v[46:47]
	v_mul_f32_e32 v89, v32, v32
	v_mul_f32_e32 v90, v33, v33
	v_pk_fma_f32 v[74:75], v[34:35], v[34:35], v[74:75] op_sel_hi:[1,1,0]
	v_pk_fma_f32 v[76:77], v[36:37], v[36:37], v[76:77] op_sel_hi:[1,1,0]
	v_pk_add_f32 v[66:67], v[78:79], v[66:67]
	v_pk_mov_b32 v[78:79], v[80:81], v[64:65] op_sel:[1,0]
	v_mov_b32_e32 v81, v65
	v_pk_add_f32 v[64:65], v[82:83], v[72:73]
	v_pk_mov_b32 v[72:73], v[84:85], v[70:71] op_sel:[1,0]
	v_mov_b32_e32 v85, v71
	v_mul_f32_e32 v87, v31, v31
	s_waitcnt vmcnt(0)
	v_mul_f32_e32 v86, v55, v55
	v_mul_f32_e32 v88, v57, v57
	v_mov_b32_e32 v75, v89
	v_mov_b32_e32 v77, v90
	v_pk_add_f32 v[78:79], v[78:79], v[80:81]
	v_pk_add_f32 v[72:73], v[72:73], v[84:85]
	v_mul_f32_e32 v17, v30, v30
	v_mul_f32_e32 v91, v50, v50
	v_mul_f32_e32 v92, v51, v51
	v_mul_f32_e32 v93, v52, v52
	v_mul_f32_e32 v94, v53, v53
	v_pk_fma_f32 v[70:71], v[54:55], v[54:55], v[86:87] op_sel_hi:[1,1,0]
	v_pk_fma_f32 v[82:83], v[56:57], v[56:57], v[88:89] op_sel_hi:[1,1,0]
	v_pk_add_f32 v[66:67], v[66:67], v[66:67] op_sel:[0,1] op_sel_hi:[1,0]
	v_pk_add_f32 v[64:65], v[64:65], v[64:65] op_sel:[0,1] op_sel_hi:[1,0]
	v_pk_add_f32 v[74:75], v[74:75], v[76:77]
	v_pk_add_f32 v[76:77], v[78:79], v[78:79] op_sel:[0,1] op_sel_hi:[1,0]
	v_pk_add_f32 v[72:73], v[72:73], v[72:73] op_sel:[0,1] op_sel_hi:[1,0]
	v_mov_b32_e32 v71, v93
	v_mov_b32_e32 v83, v94
	v_mov_b32_e32 v67, v17
	v_mov_b32_e32 v65, v87
	v_mov_b32_e32 v77, v91
	v_mov_b32_e32 v73, v92
	v_pk_add_f32 v[70:71], v[70:71], v[82:83]
	v_pk_add_f32 v[64:65], v[66:67], v[64:65]
	v_pk_add_f32 v[66:67], v[76:77], v[72:73]
	v_pk_add_f32 v[64:65], v[64:65], v[74:75]
	v_pk_add_f32 v[66:67], v[66:67], v[70:71]
	v_mov_b32_e32 v71, v64
	v_mov_b32_e32 v70, v66
	v_mov_b32_e32 v64, v67
	v_pk_add_f32 v[64:65], v[70:71], v[64:65]
	ds_bpermute_b32 v67, v11, v65
	ds_bpermute_b32 v66, v11, v64
	s_waitcnt lgkmcnt(0)
	v_pk_add_f32 v[64:65], v[64:65], v[66:67]
	ds_bpermute_b32 v67, v12, v65
	ds_bpermute_b32 v66, v12, v64
	s_waitcnt lgkmcnt(0)
	v_pk_add_f32 v[64:65], v[64:65], v[66:67]
	ds_bpermute_b32 v67, v13, v65
	ds_bpermute_b32 v66, v13, v64
	s_waitcnt lgkmcnt(0)
	v_pk_add_f32 v[64:65], v[64:65], v[66:67]
	ds_bpermute_b32 v67, v14, v65
	ds_bpermute_b32 v66, v14, v64
	s_waitcnt lgkmcnt(0)
	v_pk_add_f32 v[64:65], v[64:65], v[66:67]
	ds_bpermute_b32 v67, v15, v65
	ds_bpermute_b32 v66, v15, v64
	s_waitcnt lgkmcnt(0)
	v_pk_add_f32 v[64:65], v[64:65], v[66:67]
	ds_bpermute_b32 v67, v16, v65
	ds_bpermute_b32 v66, v16, v64
	s_waitcnt lgkmcnt(0)
	v_pk_add_f32 v[64:65], v[64:65], v[66:67]
	s_nop 0
	v_pk_fma_f32 v[64:65], v[64:65], s[14:15], v[10:11] op_sel_hi:[1,0,0]
	s_nop 0
	v_mul_f32_e32 v17, 0x4b800000, v65
	v_cmp_gt_f32_e64 s[0:1], s15, v65
	v_mul_f32_e32 v66, 0x4b800000, v64
	v_cmp_gt_f32_e32 vcc, s15, v64
	v_cndmask_b32_e64 v17, v65, v17, s[0:1]
	v_rsq_f32_e32 v17, v17
	v_cndmask_b32_e32 v64, v64, v66, vcc
	v_rsq_f32_e32 v65, v64
	v_mul_f32_e32 v64, 0x45800000, v17
	v_cndmask_b32_e64 v64, v17, v64, s[0:1]
	v_mul_f32_e32 v66, 0x45800000, v65
	v_cndmask_b32_e32 v66, v65, v66, vcc
	v_pk_mul_f32 v[22:23], v[64:65], v[22:23] op_sel_hi:[0,1]
	v_pk_mul_f32 v[24:25], v[64:65], v[24:25] op_sel_hi:[0,1]
	v_pk_mul_f32 v[42:43], v[66:67], v[42:43] op_sel_hi:[0,1]
	v_pk_mul_f32 v[44:45], v[66:67], v[44:45] op_sel_hi:[0,1]
	v_pk_mul_f32 v[24:25], v[24:25], v[98:99]
	v_pk_mul_f32 v[22:23], v[22:23], v[96:97]
	v_pk_mul_f32 v[20:21], v[44:45], v[98:99]
	v_pk_mul_f32 v[18:19], v[42:43], v[96:97]
	v_cvt_pk_bf16_f32 v22, v22, v23
	v_cvt_pk_bf16_f32 v23, v24, v25
	v_cvt_pk_bf16_f32 v18, v18, v19
	v_cvt_pk_bf16_f32 v19, v20, v21
	global_store_dwordx2 v[62:63], v[22:23], off
	global_store_dwordx2 v[68:69], v[18:19], off
	v_pk_mul_f32 v[22:23], v[64:65], v[26:27] op_sel_hi:[0,1]
	v_pk_mul_f32 v[24:25], v[64:65], v[28:29] op_sel_hi:[0,1]
	v_pk_mul_f32 v[26:27], v[66:67], v[46:47] op_sel_hi:[0,1]
	v_pk_mul_f32 v[28:29], v[66:67], v[48:49] op_sel_hi:[0,1]
	s_lshl_b64 s[0:1], s[56:57], 9
	v_pk_mul_f32 v[30:31], v[64:65], v[30:31] op_sel_hi:[0,1]
	v_pk_mul_f32 v[32:33], v[64:65], v[32:33] op_sel_hi:[0,1]
	s_add_i32 s56, s28, s58
	v_pk_mul_f32 v[24:25], v[24:25], v[102:103]
	v_pk_mul_f32 v[22:23], v[22:23], v[100:101]
	v_pk_mul_f32 v[20:21], v[28:29], v[102:103]
	v_pk_mul_f32 v[18:19], v[26:27], v[100:101]
	v_cvt_pk_bf16_f32 v22, v22, v23
	v_cvt_pk_bf16_f32 v23, v24, v25
	v_cvt_pk_bf16_f32 v18, v18, v19
	v_cvt_pk_bf16_f32 v19, v20, v21
	global_store_dwordx2 v[62:63], v[22:23], off offset:512
	global_store_dwordx2 v[68:69], v[18:19], off offset:512
	v_pk_mul_f32 v[22:23], v[64:65], v[34:35] op_sel_hi:[0,1]
	v_pk_mul_f32 v[24:25], v[64:65], v[36:37] op_sel_hi:[0,1]
	v_pk_mul_f32 v[26:27], v[66:67], v[54:55] op_sel_hi:[0,1]
	v_pk_mul_f32 v[28:29], v[66:67], v[56:57] op_sel_hi:[0,1]
	v_pk_mul_f32 v[34:35], v[66:67], v[50:51] op_sel_hi:[0,1]
	v_pk_mul_f32 v[36:37], v[66:67], v[52:53] op_sel_hi:[0,1]
	v_pk_mul_f32 v[24:25], v[24:25], v[106:107]
	v_pk_mul_f32 v[22:23], v[22:23], v[104:105]
	v_pk_mul_f32 v[20:21], v[28:29], v[106:107]
	v_pk_mul_f32 v[18:19], v[26:27], v[104:105]
	v_cvt_pk_bf16_f32 v22, v22, v23
	v_cvt_pk_bf16_f32 v23, v24, v25
	v_cvt_pk_bf16_f32 v18, v18, v19
	v_cvt_pk_bf16_f32 v19, v20, v21
	global_store_dwordx2 v[62:63], v[22:23], off offset:1024
	global_store_dwordx2 v[68:69], v[18:19], off offset:1024
	v_lshl_add_u64 v[22:23], v[0:1], 0, s[0:1]
	s_lshl_b64 s[0:1], s[16:17], 9
	s_cmpk_gt_i32 s56, 0x3fff
	v_lshl_add_u64 v[24:25], v[0:1], 0, s[0:1]
	v_cvt_pk_bf16_f32 v26, v38, v39
	v_cvt_pk_bf16_f32 v27, v40, v41
	v_cvt_pk_bf16_f32 v28, v58, v59
	v_cvt_pk_bf16_f32 v29, v60, v61
	v_pk_mul_f32 v[32:33], v[32:33], v[110:111]
	v_pk_mul_f32 v[30:31], v[30:31], v[108:109]
	v_pk_mul_f32 v[20:21], v[36:37], v[110:111]
	v_pk_mul_f32 v[18:19], v[34:35], v[108:109]
	v_cvt_pk_bf16_f32 v30, v30, v31
	v_cvt_pk_bf16_f32 v31, v32, v33
	v_cvt_pk_bf16_f32 v18, v18, v19
	v_cvt_pk_bf16_f32 v19, v20, v21
	global_store_dwordx2 v[62:63], v[30:31], off offset:1536
	global_store_dwordx2 v[68:69], v[18:19], off offset:1536
	global_store_dwordx2 v[22:23], v[26:27], off
	global_store_dwordx2 v[24:25], v[28:29], off
	s_cbranch_scc0 .LBB0_38
